# rope / qk-norm phase: in-place row stores back to write-back (the two 32-byte halves of a block merge in L2), L2 written back by the last workgroup of each XCD at that barrier
# baseline (speedup 1.0000x reference)
.LBB0_991:
	s_waitcnt lgkmcnt(0)
	s_add_i32 s14, s2, s88
	s_cmpk_gt_i32 s14, 0x23ff
	s_cselect_b32 s14, s2, s14
	s_ashr_i32 s15, s14, 31
	s_lshl_b64 s[14:15], s[14:15], 13
	v_readlane_b32 s20, v253, 56
	v_readlane_b32 s21, v253, 57
	s_add_u32 s20, s20, s14
	s_addc_u32 s21, s21, s15
	v_lshl_add_u64 v[116:117], s[20:21], 0, v[176:177]
	v_mov_b32_e32 v119, v177
	v_mov_b32_e32 v118, v12
	v_lshl_add_u64 v[116:117], v[116:117], 0, v[118:119]
	v_mov_b32_e32 v118, v14
	v_lshl_add_u64 v[116:117], v[116:117], 0, v[118:119]
	s_mov_b64 s[22:23], 0x1600
	v_lshl_add_u64 v[120:121], v[116:117], 0, s[22:23]
	s_mov_b64 s[22:23], 0x1000
	v_lshl_add_u64 v[116:117], v[116:117], 0, s[22:23]
	global_load_dwordx4 v[100:103], v[116:117], off offset:1536
	global_load_dwordx4 v[104:107], v[120:121], off offset:64
	global_load_dword v124, v[8:9], off
	v_lshl_add_u64 v[122:123], v[10:11], 0, s[14:15]
	global_load_dwordx4 v[126:129], v[122:123], off
	global_load_dwordx4 v[130:133], v[122:123], off offset:32
	global_load_dwordx4 v[108:111], v[122:123], off offset:2048
	global_load_dwordx4 v[112:115], v[122:123], off offset:2080
	v_add_f32_e32 v13, v15, v71
	v_fmamk_f32 v13, v13, 0x3c000000, v215
	v_mul_f32_e32 v15, 0x4f800000, v13
	v_cmp_gt_f32_e32 vcc, s92, v13
	s_add_i32 s2, s2, s88
	s_cmpk_gt_i32 s2, 0x23ff
	v_cndmask_b32_e32 v13, v13, v15, vcc
	v_sqrt_f32_e32 v15, v13
	s_nop 0
	v_add_u32_e32 v71, -1, v15
	v_fma_f32 v73, -v71, v15, v13
	v_add_u32_e32 v72, 1, v15
	v_cmp_ge_f32_e64 s[4:5], 0, v73
	s_nop 1
	v_cndmask_b32_e64 v71, v15, v71, s[4:5]
	v_fma_f32 v15, -v72, v15, v13
	v_cmp_lt_f32_e64 s[4:5], 0, v15
	s_nop 1
	v_cndmask_b32_e64 v15, v71, v72, s[4:5]
	v_mul_f32_e32 v71, 0x37800000, v15
	v_cndmask_b32_e32 v15, v15, v71, vcc
	v_cmp_class_f32_e32 vcc, v13, v216
	s_nop 1
	v_cndmask_b32_e32 v13, v15, v13, vcc
	v_div_scale_f32 v15, s[4:5], v13, v13, 1.0
	v_rcp_f32_e32 v71, v15
	s_nop 0
	v_fma_f32 v72, -v15, v71, 1.0
	v_fmac_f32_e32 v71, v72, v71
	v_div_scale_f32 v72, vcc, 1.0, v13, 1.0
	v_mul_f32_e32 v73, v72, v71
	v_fma_f32 v74, -v15, v73, v72
	v_fmac_f32_e32 v73, v74, v71
	v_fma_f32 v15, -v15, v73, v72
	v_div_fmas_f32 v15, v15, v71, v73
	v_div_fixup_f32 v72, v15, v13, 1.0
	v_pk_mul_f32 v[18:19], v[72:73], v[18:19] op_sel_hi:[0,1]
	s_waitcnt vmcnt(13)
	v_pk_mul_f32 v[18:19], v[18:19], v[46:47]
	v_pk_mul_f32 v[16:17], v[72:73], v[16:17] op_sel_hi:[0,1]
	v_pk_mul_f32 v[46:47], v[18:19], v[48:49] op_sel:[1,0] op_sel_hi:[0,1]
	v_pk_mul_f32 v[18:19], v[18:19], v[48:49]
	s_waitcnt vmcnt(11)
	v_pk_mul_f32 v[48:49], v[16:17], v[50:51]
	v_pk_mul_f32 v[16:17], v[72:73], v[26:27] op_sel_hi:[0,1]
	v_pk_mul_f32 v[2:3], v[72:73], v[2:3] op_sel_hi:[0,1]
	v_pk_mul_f32 v[16:17], v[16:17], v[24:25]
	v_pk_mul_f32 v[2:3], v[2:3], v[34:35]
	v_pk_mul_f32 v[24:25], v[16:17], v[32:33] op_sel:[1,0] op_sel_hi:[0,1]
	v_pk_mul_f32 v[26:27], v[2:3], v[28:29] op_sel:[1,0] op_sel_hi:[0,1]
	v_pk_mul_f32 v[6:7], v[72:73], v[6:7] op_sel_hi:[0,1]
	v_pk_mul_f32 v[4:5], v[72:73], v[4:5] op_sel_hi:[0,1]
	v_pk_mul_f32 v[16:17], v[16:17], v[32:33]
	v_mov_b32_e32 v32, v24
	v_mov_b32_e32 v33, v26
	v_mov_b32_e32 v26, v25
	v_pk_mul_f32 v[2:3], v[2:3], v[28:29]
	v_pk_mul_f32 v[6:7], v[6:7], v[40:41]
	v_pk_mul_f32 v[4:5], v[4:5], v[44:45]
	v_pk_add_f32 v[24:25], v[32:33], v[26:27] neg_lo:[0,1] neg_hi:[0,1]
	v_mov_b32_e32 v26, v16
	v_mov_b32_e32 v27, v2
	v_mov_b32_e32 v2, v17
	v_pk_mul_f32 v[40:41], v[6:7], v[42:43] op_sel:[1,0] op_sel_hi:[0,1]
	v_pk_add_f32 v[16:17], v[26:27], v[2:3]
	v_cvt_pk_bf16_f32 v2, v24, v25
	v_pk_mul_f32 v[24:25], v[4:5], v[30:31] op_sel:[1,0] op_sel_hi:[0,1]
	v_pk_mul_f32 v[6:7], v[6:7], v[42:43]
	v_mov_b32_e32 v26, v40
	v_mov_b32_e32 v27, v24
	v_mov_b32_e32 v24, v41
	v_pk_mul_f32 v[4:5], v[4:5], v[30:31]
	v_pk_add_f32 v[24:25], v[26:27], v[24:25] neg_lo:[0,1] neg_hi:[0,1]
	v_mov_b32_e32 v26, v6
	v_mov_b32_e32 v27, v4
	v_mov_b32_e32 v4, v7
	v_pk_add_f32 v[4:5], v[26:27], v[4:5]
	v_cvt_pk_bf16_f32 v16, v16, v17
	v_cvt_pk_bf16_f32 v17, v4, v5
	v_pk_mul_f32 v[4:5], v[48:49], v[36:37] op_sel:[1,0] op_sel_hi:[0,1]
	v_mov_b32_e32 v6, v46
	v_mov_b32_e32 v7, v4
	v_mov_b32_e32 v4, v47
	v_pk_add_f32 v[4:5], v[6:7], v[4:5] neg_lo:[0,1] neg_hi:[0,1]
	v_pk_mul_f32 v[6:7], v[48:49], v[36:37]
	v_pk_mul_f32 v[22:23], v[72:73], v[22:23] op_sel_hi:[0,1]
	v_pk_mul_f32 v[20:21], v[72:73], v[20:21] op_sel_hi:[0,1]
	v_cvt_pk_bf16_f32 v3, v24, v25
	v_mov_b32_e32 v24, v18
	v_mov_b32_e32 v25, v6
	v_mov_b32_e32 v6, v19
	s_waitcnt vmcnt(9)
	v_pk_mul_f32 v[22:23], v[22:23], v[52:53]
	s_waitcnt vmcnt(7)
	v_pk_mul_f32 v[20:21], v[20:21], v[56:57]
	v_pk_add_f32 v[6:7], v[24:25], v[6:7]
	v_pk_mul_f32 v[52:53], v[22:23], v[54:55] op_sel:[1,0] op_sel_hi:[0,1]
	v_cvt_pk_bf16_f32 v18, v6, v7
	v_pk_mul_f32 v[6:7], v[20:21], v[38:39] op_sel:[1,0] op_sel_hi:[0,1]
	v_pk_mul_f32 v[22:23], v[22:23], v[54:55]
	v_mov_b32_e32 v24, v52
	v_mov_b32_e32 v25, v6
	v_mov_b32_e32 v6, v53
	v_pk_mul_f32 v[20:21], v[20:21], v[38:39]
	v_pk_add_f32 v[6:7], v[24:25], v[6:7] neg_lo:[0,1] neg_hi:[0,1]
	v_mov_b32_e32 v24, v22
	v_mov_b32_e32 v25, v20
	v_mov_b32_e32 v20, v23
	v_pk_add_f32 v[20:21], v[24:25], v[20:21]
	v_cvt_pk_bf16_f32 v4, v4, v5
	v_cvt_pk_bf16_f32 v5, v6, v7
	v_cvt_pk_bf16_f32 v19, v20, v21
	global_store_dwordx4 v[0:1], v[2:5], off
	global_store_dwordx4 v[0:1], v[16:19], off offset:64
	s_cbranch_scc1 .LBB0_1012

.Lp3_loaded:
	v_and_b32_e32 v23, 8, v13
	v_cvt_f32_ubyte0_e32 v18, v23
	v_mul_f32_e32 v18, 0xbf549a78, v18
	v_exp_f32_e32 v18, v18
	v_cndmask_b32_e32 v22, v25, v24, vcc
	s_mov_b64 s[12:13], 0x800
	v_cmp_lt_u32_e32 vcc, 31, v15
	v_mul_f32_e32 v18, 0.15915494, v18
	v_mul_f32_e32 v19, v22, v18
	v_floor_f32_e32 v19, v19
	v_fma_f32 v19, v22, v18, -v19
	v_sin_f32_e32 v18, v19
	v_cos_f32_e32 v20, v19
	v_or_b32_e32 v19, 1, v23
	v_cvt_f32_ubyte0_e32 v19, v19
	v_mul_f32_e32 v19, 0xbf549a78, v19
	v_exp_f32_e32 v19, v19
	v_add_u32_e32 v13, 0x200, v13
	s_or_b64 s[10:11], vcc, s[10:11]
	v_mul_f32_e32 v19, 0.15915494, v19
	v_mul_f32_e32 v21, v22, v19
	v_floor_f32_e32 v21, v21
	v_fma_f32 v21, v22, v19, -v21
	v_sin_f32_e32 v19, v21
	v_cos_f32_e32 v21, v21
	v_lshlrev_b32_e32 v26, 16, v4
	v_lshlrev_b32_e32 v28, 16, v0
	v_and_b32_e32 v29, 0xffff0000, v0
	v_and_b32_e32 v27, 0xffff0000, v4
	v_pk_mul_f32 v[30:31], v[20:21], v[28:29]
	s_nop 0
	v_pk_fma_f32 v[30:31], v[18:19], v[26:27], v[30:31]
	v_pk_mul_f32 v[18:19], v[18:19], v[28:29]
	v_lshlrev_b32_e32 v28, 16, v1
	v_pk_fma_f32 v[18:19], v[20:21], v[26:27], v[18:19] neg_lo:[0,0,1] neg_hi:[0,0,1]
	v_and_b32_e32 v29, 0xffff0000, v1
	v_cvt_pk_bf16_f32 v4, v18, v19
	v_or_b32_e32 v18, 2, v23
	v_cvt_f32_ubyte0_e32 v18, v18
	v_mul_f32_e32 v18, 0xbf549a78, v18
	v_exp_f32_e32 v18, v18
	v_cvt_pk_bf16_f32 v0, v30, v31
	v_lshlrev_b32_e32 v26, 16, v5
	v_and_b32_e32 v27, 0xffff0000, v5
	v_mul_f32_e32 v18, 0.15915494, v18
	v_mul_f32_e32 v19, v22, v18
	v_floor_f32_e32 v19, v19
	v_fma_f32 v19, v22, v18, -v19
	v_sin_f32_e32 v18, v19
	v_cos_f32_e32 v20, v19
	v_or_b32_e32 v19, 3, v23
	v_cvt_f32_ubyte0_e32 v19, v19
	v_mul_f32_e32 v19, 0xbf549a78, v19
	v_exp_f32_e32 v19, v19
	s_nop 0
	v_mul_f32_e32 v19, 0.15915494, v19
	v_mul_f32_e32 v21, v22, v19
	v_floor_f32_e32 v21, v21
	v_fma_f32 v21, v22, v19, -v21
	v_sin_f32_e32 v19, v21
	v_cos_f32_e32 v21, v21
	s_nop 0
	v_pk_mul_f32 v[30:31], v[20:21], v[28:29]
	s_nop 0
	v_pk_fma_f32 v[30:31], v[18:19], v[26:27], v[30:31]
	v_pk_mul_f32 v[18:19], v[18:19], v[28:29]
	v_lshlrev_b32_e32 v28, 16, v2
	v_pk_fma_f32 v[18:19], v[20:21], v[26:27], v[18:19] neg_lo:[0,0,1] neg_hi:[0,0,1]
	v_and_b32_e32 v29, 0xffff0000, v2
	v_cvt_pk_bf16_f32 v5, v18, v19
	v_or_b32_e32 v18, 4, v23
	v_cvt_f32_ubyte0_e32 v18, v18
	v_mul_f32_e32 v18, 0xbf549a78, v18
	v_exp_f32_e32 v18, v18
	v_cvt_pk_bf16_f32 v1, v30, v31
	v_lshlrev_b32_e32 v26, 16, v6
	v_and_b32_e32 v27, 0xffff0000, v6
	v_mul_f32_e32 v18, 0.15915494, v18
	v_mul_f32_e32 v19, v22, v18
	v_floor_f32_e32 v19, v19
	v_fma_f32 v19, v22, v18, -v19
	v_sin_f32_e32 v18, v19
	v_cos_f32_e32 v20, v19
	v_or_b32_e32 v19, 5, v23
	v_cvt_f32_ubyte0_e32 v19, v19
	v_mul_f32_e32 v19, 0xbf549a78, v19
	v_exp_f32_e32 v19, v19
	s_nop 0
	v_mul_f32_e32 v19, 0.15915494, v19
	v_mul_f32_e32 v21, v22, v19
	v_floor_f32_e32 v21, v21
	v_fma_f32 v21, v22, v19, -v21
	v_sin_f32_e32 v19, v21
	v_cos_f32_e32 v21, v21
	s_nop 0
	v_pk_mul_f32 v[30:31], v[20:21], v[28:29]
	s_nop 0
	v_pk_fma_f32 v[30:31], v[18:19], v[26:27], v[30:31]
	v_pk_mul_f32 v[18:19], v[18:19], v[28:29]
	v_cvt_pk_bf16_f32 v2, v30, v31
	v_pk_fma_f32 v[18:19], v[20:21], v[26:27], v[18:19] neg_lo:[0,0,1] neg_hi:[0,0,1]
	v_lshlrev_b32_e32 v26, 16, v3
	v_cvt_pk_bf16_f32 v6, v18, v19
	v_or_b32_e32 v18, 6, v23
	v_cvt_f32_ubyte0_e32 v18, v18
	v_mul_f32_e32 v18, 0xbf549a78, v18
	v_exp_f32_e32 v18, v18
	v_and_b32_e32 v27, 0xffff0000, v3
	v_mul_f32_e32 v18, 0.15915494, v18
	v_mul_f32_e32 v19, v22, v18
	v_floor_f32_e32 v19, v19
	v_fma_f32 v19, v22, v18, -v19
	v_sin_f32_e32 v18, v19
	v_cos_f32_e32 v20, v19
	v_or_b32_e32 v19, 7, v23
	v_cvt_f32_ubyte0_e32 v19, v19
	v_mul_f32_e32 v19, 0xbf549a78, v19
	v_exp_f32_e32 v19, v19
	v_and_b32_e32 v23, 0xffff0000, v7
	v_mul_f32_e32 v19, 0.15915494, v19
	v_mul_f32_e32 v21, v22, v19
	v_floor_f32_e32 v21, v21
	v_fma_f32 v21, v22, v19, -v21
	v_sin_f32_e32 v19, v21
	v_cos_f32_e32 v21, v21
	v_lshlrev_b32_e32 v22, 16, v7
	v_pk_mul_f32 v[28:29], v[20:21], v[26:27]
	s_nop 0
	v_pk_fma_f32 v[28:29], v[18:19], v[22:23], v[28:29]
	v_pk_mul_f32 v[18:19], v[18:19], v[26:27]
	v_cvt_pk_bf16_f32 v3, v28, v29
	v_pk_fma_f32 v[18:19], v[20:21], v[22:23], v[18:19] neg_lo:[0,0,1] neg_hi:[0,0,1]
	s_nop 0
	v_cvt_pk_bf16_f32 v7, v18, v19
	global_store_dwordx4 v[16:17], v[4:7], off
	global_store_dwordx4 v[16:17], v[0:3], off offset:32
	v_lshl_add_u64 v[16:17], v[16:17], 0, s[12:13]
	s_nop 0
	v_add_u32_e32 v0, 64, v15
	v_mov_b32_e32 v15, v0
	s_andn2_b64 exec, exec, s[10:11]
	s_cbranch_execnz .LBB0_994
	s_or_b64 exec, exec, s[10:11]

.LBB0_1010:
	global_load_dword v57, v[8:9], off offset:28
	global_load_dword v56, v[8:9], off offset:156
	s_and_b64 vcc, exec, s[4:5]
	s_cbranch_vccnz .LBB0_991
	v_mul_f32_e32 v38, v13, v69
	v_floor_f32_e32 v38, v38
	v_fma_f32 v13, v13, v69, -v38
	v_sin_f32_e32 v39, v13
	v_cos_f32_e32 v38, v13
	s_branch .LBB0_991
.LBB0_1012:
	s_waitcnt vmcnt(0)
	s_barrier
	s_mov_b64 s[2:3], exec
	v_readlane_b32 s4, v253, 42
	v_readlane_b32 s5, v253, 43
	s_and_b64 s[4:5], s[2:3], s[4:5]
	s_mov_b64 exec, s[4:5]
	s_cbranch_execz .LBB0_1056
	v_readlane_b32 s6, v253, 39
	v_readlane_b32 s7, v253, 40
	v_readlane_b32 s8, v253, 41
	v_readlane_b32 s9, v255, 20
	v_mov_b32_e32 v0, 0x23fc0
	ds_read2_b32 v[4:5], v0 offset1:1
	s_add_i32 s9, s9, 1
	v_writelane_b32 v255, s9, 20
	s_lshl_b32 s10, s8, 8
	s_add_i32 s10, s10, 0x1400
	v_mov_b32_e32 v0, s10
	v_mov_b32_e32 v1, 1
	global_atomic_add v2, v0, v1, s[6:7] sc0
	buffer_inv sc1
	s_waitcnt vmcnt(0) lgkmcnt(0)
	v_readfirstlane_b32 s11, v2
	v_readfirstlane_b32 s15, v4
	v_readfirstlane_b32 s14, v5
	s_add_i32 s11, s11, 1
	s_mul_i32 s15, s15, s9
	s_cmp_lg_u32 s11, s15
	s_cbranch_scc1 .Lgb4_wait
	buffer_wbl2 sc1
	s_waitcnt vmcnt(0)
	s_mov_b64 exec, 0xffff
	v_mbcnt_lo_u32_b32 v3, -1, 0
	v_lshlrev_b32_e32 v3, 8, v3
	v_add_u32_e32 v3, 0x2480, v3
	v_mov_b32_e32 v1, 1
	global_atomic_add v3, v1, s[6:7]
	s_mov_b64 exec, 1
